# P2 cmp1 GEMM: global-load prefetch deepened from 1 to 2 k-steps ahead with a second register set (scripted register rename of the unrolled loop)
# baseline (speedup 1.0000x reference)
.LBB0_625:
	s_andn2_b64 vcc, exec, s[4:5]
	s_cbranch_vccnz .LBB0_620
	s_and_b32 s6, s30, 3
	s_ashr_i32 s4, s30, 7
	s_lshl_b32 s5, s6, 1
	s_add_i32 s4, s5, s4
	s_ashr_i32 s5, s4, 31
	s_lshl_b64 s[4:5], s[4:5], 22
	s_add_u32 s16, s20, s4
	s_addc_u32 s17, s21, s5
	s_cmpk_lt_u32 s30, 0x80
	s_cselect_b32 s4, s26, 0x82a0800
	s_cselect_b32 s5, s27, 0x1900000
	s_add_u32 s4, s52, s4
	s_addc_u32 s31, s53, 0
	s_lshl_b32 s6, s6, 10
	s_add_u32 s34, s4, s6
	s_addc_u32 s35, s31, 0
	s_add_u32 s4, s52, s5
	v_mov_b32_e32 v13, v238
	s_addc_u32 s5, s53, 0
	s_add_u32 s36, s4, s6
	v_ashrrev_i32_e32 v12, 3, v13
	v_and_b32_e32 v2, 0x7f, v12
	s_addc_u32 s37, s5, 0
	s_and_b32 s4, s3, 0xf00
	v_lshlrev_b32_e32 v3, 10, v2
	v_cmp_ne_u32_e32 vcc, s25, v2
	v_add_u32_e32 v6, s4, v12
	v_ashrrev_i32_e32 v0, 7, v6
	v_cndmask_b32_e32 v2, v67, v3, vcc
	v_lshlrev_b32_e32 v64, 1, v2
	v_lshlrev_b32_e32 v2, 4, v13
	v_add_u32_e32 v3, 64, v6
	v_and_b32_e32 v8, 0x70, v2
	v_ashrrev_i32_e32 v2, 7, v3
	v_and_b32_e32 v4, 0x7f, v3
	v_ashrrev_i32_e32 v3, 31, v2
	v_lshlrev_b32_e32 v5, 10, v4
	v_cmp_ne_u32_e32 vcc, s25, v4
	v_lshlrev_b64 v[2:3], 18, v[2:3]
	v_lshl_add_u64 v[2:3], s[34:35], 0, v[2:3]
	v_cndmask_b32_e32 v4, v67, v5, vcc
	v_lshlrev_b32_e32 v4, 1, v4
	v_mov_b32_e32 v5, v65
	v_lshl_add_u64 v[2:3], v[2:3], 0, v[4:5]
	v_add_u32_e32 v4, 0x80, v6
	v_ashrrev_i32_e32 v4, 7, v4
	v_add_u32_e32 v7, 0xc0, v6
	v_ashrrev_i32_e32 v1, 31, v0
	v_ashrrev_i32_e32 v5, 31, v4
	v_ashrrev_i32_e32 v6, 7, v7
	v_and_b32_e32 v10, 0x7f, v7
	v_lshlrev_b64 v[0:1], 18, v[0:1]
	v_lshlrev_b64 v[4:5], 18, v[4:5]
	v_ashrrev_i32_e32 v7, 31, v6
	v_lshlrev_b32_e32 v11, 10, v10
	v_cmp_ne_u32_e32 vcc, s25, v10
	s_and_b32 s5, s3, 0x80
	v_lshl_add_u64 v[0:1], s[34:35], 0, v[0:1]
	v_lshl_add_u64 v[4:5], s[34:35], 0, v[4:5]
	v_cndmask_b32_e32 v10, v67, v11, vcc
	v_lshlrev_b64 v[6:7], 18, v[6:7]
	v_lshl_add_u64 v[0:1], v[0:1], 0, v[64:65]
	v_lshl_add_u64 v[4:5], v[4:5], 0, v[64:65]
	v_lshl_add_u64 v[6:7], s[34:35], 0, v[6:7]
	v_lshlrev_b32_e32 v64, 1, v10
	v_add_u32_e32 v10, s5, v12
	v_mov_b32_e32 v9, v65
	v_lshl_add_u64 v[6:7], v[6:7], 0, v[64:65]
	v_ashrrev_i32_e32 v11, 31, v10
	v_lshl_add_u64 v[0:1], v[0:1], 0, v[8:9]
	v_lshl_add_u64 v[2:3], v[2:3], 0, v[8:9]
	v_lshl_add_u64 v[4:5], v[4:5], 0, v[8:9]
	v_lshl_add_u64 v[6:7], v[6:7], 0, v[8:9]
	v_lshl_add_u64 v[8:9], s[36:37], 0, v[8:9]
	v_lshlrev_b64 v[10:11], 12, v[10:11]
	v_lshl_add_u64 v[8:9], v[8:9], 0, v[10:11]
	v_add_co_u32_e32 v10, vcc, s28, v8
	v_readfirstlane_b32 s6, v13
	s_nop 0
	v_addc_co_u32_e32 v11, vcc, 0, v9, vcc
	global_load_dwordx4 v[14:17], v[8:9], off
	global_load_dwordx4 v[18:21], v[10:11], off
	global_load_dwordx4 v[22:25], v[0:1], off
	global_load_dwordx4 v[26:29], v[2:3], off
	global_load_dwordx4 v[30:33], v[4:5], off
	global_load_dwordx4 v[34:37], v[6:7], off
	v_lshrrev_b32_e32 v10, 1, v12
	v_xor_b32_e32 v10, v10, v13
	v_lshlrev_b32_e32 v10, 4, v10
	v_and_b32_e32 v10, 0x70, v10
	v_lshl_or_b32 v64, v12, 7, v10
	v_add_u32_e32 v12, 0, v64
	v_lshl_add_u64 v[10:11], v[8:9], 0, s[8:9]
	s_ashr_i32 s31, s6, 1
	v_bfe_u32 v40, v13, 4, 2
	s_and_b32 s6, s6, 64
	s_andn2_b32 s31, s31, 63
	s_waitcnt vmcnt(5)
	ds_write_b128 v12, v[14:17] offset:32768
	s_waitcnt vmcnt(4)
	ds_write_b128 v12, v[18:21] offset:40960
	s_waitcnt vmcnt(3)
	ds_write_b128 v12, v[22:25]
	s_waitcnt vmcnt(2)
	ds_write_b128 v12, v[26:29] offset:8192
	s_waitcnt vmcnt(1)
	ds_write_b128 v12, v[30:33] offset:16384
	s_waitcnt vmcnt(0)
	ds_write_b128 v12, v[34:37] offset:24576
	s_waitcnt lgkmcnt(0)
	s_barrier
	global_load_dwordx4 v[16:19], v[0:1], off offset:128
	global_load_dwordx4 v[20:23], v[2:3], off offset:128
	global_load_dwordx4 v[24:27], v[4:5], off offset:128
	global_load_dwordx4 v[28:31], v[6:7], off offset:128
	global_load_dwordx4 v[32:35], v[8:9], off offset:128
	global_load_dwordx4 v[36:39], v[10:11], off offset:128
	global_load_dwordx4 v[200:203], v[0:1], off offset:256
	global_load_dwordx4 v[204:207], v[2:3], off offset:256
	global_load_dwordx4 v[208:211], v[4:5], off offset:256
	global_load_dwordx4 v[212:215], v[6:7], off offset:256
	global_load_dwordx4 v[216:219], v[8:9], off offset:256
	global_load_dwordx4 v[220:223], v[10:11], off offset:256
	v_and_b32_e32 v14, 15, v13
	v_lshrrev_b32_e32 v15, 4, v13
	v_bfe_u32 v13, v13, 1, 3
	v_bitop3_b32 v15, v15, v13, 3 bitop3:0x6c
	v_bitop3_b32 v112, v40, v13, 4 bitop3:0x36
	v_or_b32_e32 v13, s31, v14
	v_or_b32_e32 v14, s6, v14
	v_lshlrev_b32_e32 v15, 4, v15
	v_add_u32_e32 v44, 0, v15
	v_lshlrev_b32_e32 v132, 7, v14
	v_add_u32_e32 v133, v44, v132
	v_lshlrev_b32_e32 v14, 7, v13
	ds_read_b128 v[40:43], v133 offset:32768
	v_add_u32_e32 v13, v44, v14
	ds_read_b128 v[44:47], v133 offset:34816
	ds_read_b128 v[48:51], v13
	ds_read_b128 v[52:55], v13 offset:2048
	ds_read_b128 v[60:63], v133 offset:36864
	ds_read_b128 v[72:75], v133 offset:38912
	ds_read_b128 v[92:95], v13 offset:4096
	ds_read_b128 v[96:99], v13 offset:6144
	v_lshlrev_b32_e32 v134, 4, v112
	v_add_u32_e32 v116, 0, v134
	v_add_u32_e32 v135, v116, v132
	s_waitcnt lgkmcnt(5)
	v_mfma_f32_16x16x32_bf16 v[56:59], v[40:43], v[48:51], 0
	ds_read_b128 v[112:115], v135 offset:32768
	v_add_u32_e32 v14, v116, v14
	v_mfma_f32_16x16x32_bf16 v[68:71], v[44:47], v[48:51], 0
	s_waitcnt lgkmcnt(4)
	v_mfma_f32_16x16x32_bf16 v[76:79], v[60:63], v[48:51], 0
	s_waitcnt lgkmcnt(3)
	v_mfma_f32_16x16x32_bf16 v[48:51], v[72:75], v[48:51], 0
	v_mfma_f32_16x16x32_bf16 v[80:83], v[40:43], v[52:55], 0
	v_mfma_f32_16x16x32_bf16 v[84:87], v[44:47], v[52:55], 0
	v_mfma_f32_16x16x32_bf16 v[88:91], v[60:63], v[52:55], 0
	v_mfma_f32_16x16x32_bf16 v[52:55], v[72:75], v[52:55], 0
	s_waitcnt lgkmcnt(2)
	v_mfma_f32_16x16x32_bf16 v[100:103], v[40:43], v[92:95], 0
	v_mfma_f32_16x16x32_bf16 v[104:107], v[44:47], v[92:95], 0
	v_mfma_f32_16x16x32_bf16 v[108:111], v[60:63], v[92:95], 0
	v_mfma_f32_16x16x32_bf16 v[92:95], v[72:75], v[92:95], 0
	s_waitcnt lgkmcnt(1)
	v_mfma_f32_16x16x32_bf16 v[40:43], v[40:43], v[96:99], 0
	v_mfma_f32_16x16x32_bf16 v[44:47], v[44:47], v[96:99], 0
	v_mfma_f32_16x16x32_bf16 v[60:63], v[60:63], v[96:99], 0
	v_mfma_f32_16x16x32_bf16 v[72:75], v[72:75], v[96:99], 0
	ds_read_b128 v[96:99], v135 offset:34816
	ds_read_b128 v[116:119], v14
	ds_read_b128 v[120:123], v14 offset:2048
	ds_read_b128 v[124:127], v135 offset:36864
	ds_read_b128 v[128:131], v135 offset:38912
	s_waitcnt lgkmcnt(3)
	v_mfma_f32_16x16x32_bf16 v[56:59], v[112:115], v[116:119], v[56:59]
	v_mfma_f32_16x16x32_bf16 v[68:71], v[96:99], v[116:119], v[68:71]
	s_waitcnt lgkmcnt(1)
	v_mfma_f32_16x16x32_bf16 v[76:79], v[124:127], v[116:119], v[76:79]
	s_waitcnt lgkmcnt(0)
	v_mfma_f32_16x16x32_bf16 v[48:51], v[128:131], v[116:119], v[48:51]
	v_mfma_f32_16x16x32_bf16 v[80:83], v[112:115], v[120:123], v[80:83]
	v_mfma_f32_16x16x32_bf16 v[84:87], v[96:99], v[120:123], v[84:87]
	v_mfma_f32_16x16x32_bf16 v[88:91], v[124:127], v[120:123], v[88:91]
	v_mfma_f32_16x16x32_bf16 v[52:55], v[128:131], v[120:123], v[52:55]
	ds_read_b128 v[116:119], v14 offset:4096
	ds_read_b128 v[120:123], v14 offset:6144
	s_waitcnt lgkmcnt(1)
	v_mfma_f32_16x16x32_bf16 v[100:103], v[112:115], v[116:119], v[100:103]
	v_mfma_f32_16x16x32_bf16 v[104:107], v[96:99], v[116:119], v[104:107]
	v_mfma_f32_16x16x32_bf16 v[108:111], v[124:127], v[116:119], v[108:111]
	v_mfma_f32_16x16x32_bf16 v[92:95], v[128:131], v[116:119], v[92:95]
	s_waitcnt lgkmcnt(0)
	v_mfma_f32_16x16x32_bf16 v[40:43], v[112:115], v[120:123], v[40:43]
	v_mfma_f32_16x16x32_bf16 v[44:47], v[96:99], v[120:123], v[44:47]
	v_mfma_f32_16x16x32_bf16 v[60:63], v[124:127], v[120:123], v[60:63]
	v_mfma_f32_16x16x32_bf16 v[72:75], v[128:131], v[120:123], v[72:75]
	v_add_u32_e32 v64, s48, v64
	v_add_u32_e32 v136, 0xc000, v12
	s_waitcnt vmcnt(11)
	ds_write_b128 v12, v[16:19] offset:49152
	s_waitcnt vmcnt(10)
	ds_write_b128 v12, v[20:23] offset:57344
	s_waitcnt vmcnt(9)
	ds_write_b128 v136, v[24:27] offset:16384
	s_waitcnt vmcnt(8)
	ds_write_b128 v136, v[28:31] offset:24576
	s_waitcnt vmcnt(7)
	ds_write_b128 v64, v[32:35]
	s_waitcnt vmcnt(6)
	ds_write_b128 v64, v[36:39] offset:8192
	s_waitcnt lgkmcnt(0)
	s_barrier
	global_load_dwordx4 v[16:19], v[0:1], off offset:384
	global_load_dwordx4 v[20:23], v[2:3], off offset:384
	global_load_dwordx4 v[24:27], v[4:5], off offset:384
	global_load_dwordx4 v[28:31], v[6:7], off offset:384
	global_load_dwordx4 v[32:35], v[8:9], off offset:384
	global_load_dwordx4 v[36:39], v[10:11], off offset:384
	v_add3_u32 v15, s48, v15, v132
	ds_read_b128 v[96:99], v15
	ds_read_b128 v[112:115], v15 offset:2048
	ds_read_b128 v[116:119], v13 offset:49152
	ds_read_b128 v[120:123], v13 offset:51200
	ds_read_b128 v[124:127], v15 offset:4096
	ds_read_b128 v[128:131], v15 offset:6144
	v_add3_u32 v132, s48, v134, v132
	s_waitcnt lgkmcnt(3)
	v_mfma_f32_16x16x32_bf16 v[56:59], v[96:99], v[116:119], v[56:59]
	v_mfma_f32_16x16x32_bf16 v[68:71], v[112:115], v[116:119], v[68:71]
	s_waitcnt lgkmcnt(1)
	v_mfma_f32_16x16x32_bf16 v[76:79], v[124:127], v[116:119], v[76:79]
	s_waitcnt lgkmcnt(0)
	v_mfma_f32_16x16x32_bf16 v[48:51], v[128:131], v[116:119], v[48:51]
	v_mfma_f32_16x16x32_bf16 v[80:83], v[96:99], v[120:123], v[80:83]
	v_mfma_f32_16x16x32_bf16 v[84:87], v[112:115], v[120:123], v[84:87]
	v_mfma_f32_16x16x32_bf16 v[88:91], v[124:127], v[120:123], v[88:91]
	v_mfma_f32_16x16x32_bf16 v[52:55], v[128:131], v[120:123], v[52:55]
	ds_read_b128 v[116:119], v13 offset:53248
	ds_read_b128 v[120:123], v13 offset:55296
	s_waitcnt lgkmcnt(1)
	v_mfma_f32_16x16x32_bf16 v[100:103], v[96:99], v[116:119], v[100:103]
	v_mfma_f32_16x16x32_bf16 v[104:107], v[112:115], v[116:119], v[104:107]
	v_mfma_f32_16x16x32_bf16 v[108:111], v[124:127], v[116:119], v[108:111]
	v_mfma_f32_16x16x32_bf16 v[92:95], v[128:131], v[116:119], v[92:95]
	s_waitcnt lgkmcnt(0)
	v_mfma_f32_16x16x32_bf16 v[40:43], v[96:99], v[120:123], v[40:43]
	ds_read_b128 v[96:99], v132
	v_mfma_f32_16x16x32_bf16 v[44:47], v[112:115], v[120:123], v[44:47]
	v_mfma_f32_16x16x32_bf16 v[60:63], v[124:127], v[120:123], v[60:63]
	v_mfma_f32_16x16x32_bf16 v[72:75], v[128:131], v[120:123], v[72:75]
	ds_read_b128 v[112:115], v132 offset:2048
	ds_read_b128 v[116:119], v14 offset:49152
	ds_read_b128 v[120:123], v14 offset:51200
	ds_read_b128 v[124:127], v132 offset:4096
	ds_read_b128 v[128:131], v132 offset:6144
	s_waitcnt lgkmcnt(3)
	v_mfma_f32_16x16x32_bf16 v[56:59], v[96:99], v[116:119], v[56:59]
	v_mfma_f32_16x16x32_bf16 v[68:71], v[112:115], v[116:119], v[68:71]
	s_waitcnt lgkmcnt(1)
	v_mfma_f32_16x16x32_bf16 v[76:79], v[124:127], v[116:119], v[76:79]
	s_waitcnt lgkmcnt(0)
	v_mfma_f32_16x16x32_bf16 v[48:51], v[128:131], v[116:119], v[48:51]
	v_mfma_f32_16x16x32_bf16 v[80:83], v[96:99], v[120:123], v[80:83]
	v_mfma_f32_16x16x32_bf16 v[84:87], v[112:115], v[120:123], v[84:87]
	v_mfma_f32_16x16x32_bf16 v[88:91], v[124:127], v[120:123], v[88:91]
	v_mfma_f32_16x16x32_bf16 v[52:55], v[128:131], v[120:123], v[52:55]
	ds_read_b128 v[116:119], v14 offset:53248
	ds_read_b128 v[120:123], v14 offset:55296
	s_waitcnt lgkmcnt(1)
	v_mfma_f32_16x16x32_bf16 v[100:103], v[96:99], v[116:119], v[100:103]
	v_mfma_f32_16x16x32_bf16 v[104:107], v[112:115], v[116:119], v[104:107]
	v_mfma_f32_16x16x32_bf16 v[108:111], v[124:127], v[116:119], v[108:111]
	v_mfma_f32_16x16x32_bf16 v[92:95], v[128:131], v[116:119], v[92:95]
	s_waitcnt lgkmcnt(0)
	v_mfma_f32_16x16x32_bf16 v[40:43], v[96:99], v[120:123], v[40:43]
	v_mfma_f32_16x16x32_bf16 v[44:47], v[112:115], v[120:123], v[44:47]
	v_mfma_f32_16x16x32_bf16 v[60:63], v[124:127], v[120:123], v[60:63]
	v_mfma_f32_16x16x32_bf16 v[72:75], v[128:131], v[120:123], v[72:75]
	s_waitcnt vmcnt(11)
	ds_write_b128 v12, v[200:203]
	s_waitcnt vmcnt(10)
	ds_write_b128 v12, v[204:207] offset:8192
	s_waitcnt vmcnt(9)
	ds_write_b128 v12, v[208:211] offset:16384
	s_waitcnt vmcnt(8)
	ds_write_b128 v12, v[212:215] offset:24576
	s_waitcnt vmcnt(7)
	ds_write_b128 v12, v[216:219] offset:32768
	s_waitcnt vmcnt(6)
	ds_write_b128 v12, v[220:223] offset:40960
	s_waitcnt lgkmcnt(0)
	s_barrier
	global_load_dwordx4 v[200:203], v[0:1], off offset:512
	global_load_dwordx4 v[204:207], v[2:3], off offset:512
	global_load_dwordx4 v[208:211], v[4:5], off offset:512
	global_load_dwordx4 v[212:215], v[6:7], off offset:512
	global_load_dwordx4 v[216:219], v[8:9], off offset:512
	global_load_dwordx4 v[220:223], v[10:11], off offset:512
	ds_read_b128 v[96:99], v133 offset:32768
	ds_read_b128 v[112:115], v133 offset:34816
	ds_read_b128 v[116:119], v13
	ds_read_b128 v[120:123], v13 offset:2048
	ds_read_b128 v[124:127], v133 offset:36864
	ds_read_b128 v[128:131], v133 offset:38912
	s_waitcnt lgkmcnt(3)
	v_mfma_f32_16x16x32_bf16 v[56:59], v[96:99], v[116:119], v[56:59]
	v_mfma_f32_16x16x32_bf16 v[68:71], v[112:115], v[116:119], v[68:71]
	s_waitcnt lgkmcnt(1)
	v_mfma_f32_16x16x32_bf16 v[76:79], v[124:127], v[116:119], v[76:79]
	s_waitcnt lgkmcnt(0)
	v_mfma_f32_16x16x32_bf16 v[48:51], v[128:131], v[116:119], v[48:51]
	v_mfma_f32_16x16x32_bf16 v[80:83], v[96:99], v[120:123], v[80:83]
	v_mfma_f32_16x16x32_bf16 v[84:87], v[112:115], v[120:123], v[84:87]
	v_mfma_f32_16x16x32_bf16 v[88:91], v[124:127], v[120:123], v[88:91]
	v_mfma_f32_16x16x32_bf16 v[52:55], v[128:131], v[120:123], v[52:55]
	ds_read_b128 v[116:119], v13 offset:4096
	ds_read_b128 v[120:123], v13 offset:6144
	s_waitcnt lgkmcnt(1)
	v_mfma_f32_16x16x32_bf16 v[100:103], v[96:99], v[116:119], v[100:103]
	v_mfma_f32_16x16x32_bf16 v[104:107], v[112:115], v[116:119], v[104:107]
	v_mfma_f32_16x16x32_bf16 v[108:111], v[124:127], v[116:119], v[108:111]
	v_mfma_f32_16x16x32_bf16 v[92:95], v[128:131], v[116:119], v[92:95]
	s_waitcnt lgkmcnt(0)
	v_mfma_f32_16x16x32_bf16 v[40:43], v[96:99], v[120:123], v[40:43]
	ds_read_b128 v[96:99], v135 offset:32768
	v_mfma_f32_16x16x32_bf16 v[44:47], v[112:115], v[120:123], v[44:47]
	v_mfma_f32_16x16x32_bf16 v[60:63], v[124:127], v[120:123], v[60:63]
	v_mfma_f32_16x16x32_bf16 v[72:75], v[128:131], v[120:123], v[72:75]
	ds_read_b128 v[112:115], v135 offset:34816
	ds_read_b128 v[116:119], v14
	ds_read_b128 v[120:123], v14 offset:2048
	ds_read_b128 v[124:127], v135 offset:36864
	ds_read_b128 v[128:131], v135 offset:38912
	s_waitcnt lgkmcnt(3)
	v_mfma_f32_16x16x32_bf16 v[56:59], v[96:99], v[116:119], v[56:59]
	v_mfma_f32_16x16x32_bf16 v[68:71], v[112:115], v[116:119], v[68:71]
	s_waitcnt lgkmcnt(1)
	v_mfma_f32_16x16x32_bf16 v[76:79], v[124:127], v[116:119], v[76:79]
	s_waitcnt lgkmcnt(0)
	v_mfma_f32_16x16x32_bf16 v[48:51], v[128:131], v[116:119], v[48:51]
	v_mfma_f32_16x16x32_bf16 v[80:83], v[96:99], v[120:123], v[80:83]
	v_mfma_f32_16x16x32_bf16 v[84:87], v[112:115], v[120:123], v[84:87]
	v_mfma_f32_16x16x32_bf16 v[88:91], v[124:127], v[120:123], v[88:91]
	v_mfma_f32_16x16x32_bf16 v[52:55], v[128:131], v[120:123], v[52:55]
	ds_read_b128 v[116:119], v14 offset:4096
	ds_read_b128 v[120:123], v14 offset:6144
	s_waitcnt lgkmcnt(1)
	v_mfma_f32_16x16x32_bf16 v[100:103], v[96:99], v[116:119], v[100:103]
	v_mfma_f32_16x16x32_bf16 v[104:107], v[112:115], v[116:119], v[104:107]
	v_mfma_f32_16x16x32_bf16 v[108:111], v[124:127], v[116:119], v[108:111]
	v_mfma_f32_16x16x32_bf16 v[92:95], v[128:131], v[116:119], v[92:95]
	s_waitcnt lgkmcnt(0)
	v_mfma_f32_16x16x32_bf16 v[40:43], v[96:99], v[120:123], v[40:43]
	v_mfma_f32_16x16x32_bf16 v[44:47], v[112:115], v[120:123], v[44:47]
	v_mfma_f32_16x16x32_bf16 v[60:63], v[124:127], v[120:123], v[60:63]
	v_mfma_f32_16x16x32_bf16 v[72:75], v[128:131], v[120:123], v[72:75]
	s_waitcnt vmcnt(11)
	ds_write_b128 v12, v[16:19] offset:49152
	s_waitcnt vmcnt(10)
	ds_write_b128 v12, v[20:23] offset:57344
	s_waitcnt vmcnt(9)
	ds_write_b128 v136, v[24:27] offset:16384
	s_waitcnt vmcnt(8)
	ds_write_b128 v136, v[28:31] offset:24576
	s_waitcnt vmcnt(7)
	ds_write_b128 v64, v[32:35]
	s_waitcnt vmcnt(6)
	ds_write_b128 v64, v[36:39] offset:8192
	s_waitcnt lgkmcnt(0)
	s_barrier
	global_load_dwordx4 v[16:19], v[0:1], off offset:640
	global_load_dwordx4 v[20:23], v[2:3], off offset:640
	global_load_dwordx4 v[24:27], v[4:5], off offset:640
	global_load_dwordx4 v[28:31], v[6:7], off offset:640
	global_load_dwordx4 v[32:35], v[8:9], off offset:640
	global_load_dwordx4 v[36:39], v[10:11], off offset:640
	ds_read_b128 v[96:99], v15
	ds_read_b128 v[112:115], v15 offset:2048
	ds_read_b128 v[116:119], v13 offset:49152
	ds_read_b128 v[120:123], v13 offset:51200
	ds_read_b128 v[124:127], v15 offset:4096
	ds_read_b128 v[128:131], v15 offset:6144
	s_waitcnt lgkmcnt(3)
	v_mfma_f32_16x16x32_bf16 v[56:59], v[96:99], v[116:119], v[56:59]
	v_mfma_f32_16x16x32_bf16 v[68:71], v[112:115], v[116:119], v[68:71]
	s_waitcnt lgkmcnt(1)
	v_mfma_f32_16x16x32_bf16 v[76:79], v[124:127], v[116:119], v[76:79]
	s_waitcnt lgkmcnt(0)
	v_mfma_f32_16x16x32_bf16 v[48:51], v[128:131], v[116:119], v[48:51]
	v_mfma_f32_16x16x32_bf16 v[80:83], v[96:99], v[120:123], v[80:83]
	v_mfma_f32_16x16x32_bf16 v[84:87], v[112:115], v[120:123], v[84:87]
	v_mfma_f32_16x16x32_bf16 v[88:91], v[124:127], v[120:123], v[88:91]
	v_mfma_f32_16x16x32_bf16 v[52:55], v[128:131], v[120:123], v[52:55]
	ds_read_b128 v[116:119], v13 offset:53248
	ds_read_b128 v[120:123], v13 offset:55296
	s_waitcnt lgkmcnt(1)
	v_mfma_f32_16x16x32_bf16 v[100:103], v[96:99], v[116:119], v[100:103]
	v_mfma_f32_16x16x32_bf16 v[104:107], v[112:115], v[116:119], v[104:107]
	v_mfma_f32_16x16x32_bf16 v[108:111], v[124:127], v[116:119], v[108:111]
	v_mfma_f32_16x16x32_bf16 v[92:95], v[128:131], v[116:119], v[92:95]
	s_waitcnt lgkmcnt(0)
	v_mfma_f32_16x16x32_bf16 v[40:43], v[96:99], v[120:123], v[40:43]
	ds_read_b128 v[96:99], v132
	v_mfma_f32_16x16x32_bf16 v[44:47], v[112:115], v[120:123], v[44:47]
	v_mfma_f32_16x16x32_bf16 v[60:63], v[124:127], v[120:123], v[60:63]
	v_mfma_f32_16x16x32_bf16 v[72:75], v[128:131], v[120:123], v[72:75]
	ds_read_b128 v[112:115], v132 offset:2048
	ds_read_b128 v[116:119], v14 offset:49152
	ds_read_b128 v[120:123], v14 offset:51200
	ds_read_b128 v[124:127], v132 offset:4096
	ds_read_b128 v[128:131], v132 offset:6144
	s_waitcnt lgkmcnt(3)
	v_mfma_f32_16x16x32_bf16 v[56:59], v[96:99], v[116:119], v[56:59]
	v_mfma_f32_16x16x32_bf16 v[68:71], v[112:115], v[116:119], v[68:71]
	s_waitcnt lgkmcnt(1)
	v_mfma_f32_16x16x32_bf16 v[76:79], v[124:127], v[116:119], v[76:79]
	s_waitcnt lgkmcnt(0)
	v_mfma_f32_16x16x32_bf16 v[48:51], v[128:131], v[116:119], v[48:51]
	v_mfma_f32_16x16x32_bf16 v[80:83], v[96:99], v[120:123], v[80:83]
	v_mfma_f32_16x16x32_bf16 v[84:87], v[112:115], v[120:123], v[84:87]
	v_mfma_f32_16x16x32_bf16 v[88:91], v[124:127], v[120:123], v[88:91]
	v_mfma_f32_16x16x32_bf16 v[52:55], v[128:131], v[120:123], v[52:55]
	ds_read_b128 v[116:119], v14 offset:53248
	ds_read_b128 v[120:123], v14 offset:55296
	s_waitcnt lgkmcnt(1)
	v_mfma_f32_16x16x32_bf16 v[100:103], v[96:99], v[116:119], v[100:103]
	v_mfma_f32_16x16x32_bf16 v[104:107], v[112:115], v[116:119], v[104:107]
	v_mfma_f32_16x16x32_bf16 v[108:111], v[124:127], v[116:119], v[108:111]
	v_mfma_f32_16x16x32_bf16 v[92:95], v[128:131], v[116:119], v[92:95]
	s_waitcnt lgkmcnt(0)
	v_mfma_f32_16x16x32_bf16 v[40:43], v[96:99], v[120:123], v[40:43]
	v_mfma_f32_16x16x32_bf16 v[44:47], v[112:115], v[120:123], v[44:47]
	v_mfma_f32_16x16x32_bf16 v[60:63], v[124:127], v[120:123], v[60:63]
	v_mfma_f32_16x16x32_bf16 v[72:75], v[128:131], v[120:123], v[72:75]
	s_waitcnt vmcnt(11)
	ds_write_b128 v12, v[200:203]
	s_waitcnt vmcnt(10)
	ds_write_b128 v12, v[204:207] offset:8192
	s_waitcnt vmcnt(9)
	ds_write_b128 v12, v[208:211] offset:16384
	s_waitcnt vmcnt(8)
	ds_write_b128 v12, v[212:215] offset:24576
	s_waitcnt vmcnt(7)
	ds_write_b128 v12, v[216:219] offset:32768
	s_waitcnt vmcnt(6)
	ds_write_b128 v12, v[220:223] offset:40960
	s_waitcnt lgkmcnt(0)
	s_barrier
	global_load_dwordx4 v[200:203], v[0:1], off offset:768
	global_load_dwordx4 v[204:207], v[2:3], off offset:768
	global_load_dwordx4 v[208:211], v[4:5], off offset:768
	global_load_dwordx4 v[212:215], v[6:7], off offset:768
	global_load_dwordx4 v[216:219], v[8:9], off offset:768
	global_load_dwordx4 v[220:223], v[10:11], off offset:768
	ds_read_b128 v[96:99], v133 offset:32768
	ds_read_b128 v[112:115], v133 offset:34816
	ds_read_b128 v[116:119], v13
	ds_read_b128 v[120:123], v13 offset:2048
	ds_read_b128 v[124:127], v133 offset:36864
	ds_read_b128 v[128:131], v133 offset:38912
	s_waitcnt lgkmcnt(3)
	v_mfma_f32_16x16x32_bf16 v[56:59], v[96:99], v[116:119], v[56:59]
	v_mfma_f32_16x16x32_bf16 v[68:71], v[112:115], v[116:119], v[68:71]
	s_waitcnt lgkmcnt(1)
	v_mfma_f32_16x16x32_bf16 v[76:79], v[124:127], v[116:119], v[76:79]
	s_waitcnt lgkmcnt(0)
	v_mfma_f32_16x16x32_bf16 v[48:51], v[128:131], v[116:119], v[48:51]
	v_mfma_f32_16x16x32_bf16 v[80:83], v[96:99], v[120:123], v[80:83]
	v_mfma_f32_16x16x32_bf16 v[84:87], v[112:115], v[120:123], v[84:87]
	v_mfma_f32_16x16x32_bf16 v[88:91], v[124:127], v[120:123], v[88:91]
	v_mfma_f32_16x16x32_bf16 v[52:55], v[128:131], v[120:123], v[52:55]
	ds_read_b128 v[116:119], v13 offset:4096
	ds_read_b128 v[120:123], v13 offset:6144
	s_waitcnt lgkmcnt(1)
	v_mfma_f32_16x16x32_bf16 v[100:103], v[96:99], v[116:119], v[100:103]
	v_mfma_f32_16x16x32_bf16 v[104:107], v[112:115], v[116:119], v[104:107]
	v_mfma_f32_16x16x32_bf16 v[108:111], v[124:127], v[116:119], v[108:111]
	v_mfma_f32_16x16x32_bf16 v[92:95], v[128:131], v[116:119], v[92:95]
	s_waitcnt lgkmcnt(0)
	v_mfma_f32_16x16x32_bf16 v[40:43], v[96:99], v[120:123], v[40:43]
	ds_read_b128 v[96:99], v135 offset:32768
	v_mfma_f32_16x16x32_bf16 v[44:47], v[112:115], v[120:123], v[44:47]
	v_mfma_f32_16x16x32_bf16 v[60:63], v[124:127], v[120:123], v[60:63]
	v_mfma_f32_16x16x32_bf16 v[72:75], v[128:131], v[120:123], v[72:75]
	ds_read_b128 v[112:115], v135 offset:34816
	ds_read_b128 v[116:119], v14
	ds_read_b128 v[120:123], v14 offset:2048
	ds_read_b128 v[124:127], v135 offset:36864
	ds_read_b128 v[128:131], v135 offset:38912
	s_waitcnt lgkmcnt(3)
	v_mfma_f32_16x16x32_bf16 v[56:59], v[96:99], v[116:119], v[56:59]
	v_mfma_f32_16x16x32_bf16 v[68:71], v[112:115], v[116:119], v[68:71]
	s_waitcnt lgkmcnt(1)
	v_mfma_f32_16x16x32_bf16 v[76:79], v[124:127], v[116:119], v[76:79]
	s_waitcnt lgkmcnt(0)
	v_mfma_f32_16x16x32_bf16 v[48:51], v[128:131], v[116:119], v[48:51]
	v_mfma_f32_16x16x32_bf16 v[80:83], v[96:99], v[120:123], v[80:83]
	v_mfma_f32_16x16x32_bf16 v[84:87], v[112:115], v[120:123], v[84:87]
	v_mfma_f32_16x16x32_bf16 v[88:91], v[124:127], v[120:123], v[88:91]
	v_mfma_f32_16x16x32_bf16 v[52:55], v[128:131], v[120:123], v[52:55]
	ds_read_b128 v[116:119], v14 offset:4096
	ds_read_b128 v[120:123], v14 offset:6144
	s_waitcnt lgkmcnt(1)
	v_mfma_f32_16x16x32_bf16 v[100:103], v[96:99], v[116:119], v[100:103]
	v_mfma_f32_16x16x32_bf16 v[104:107], v[112:115], v[116:119], v[104:107]
	v_mfma_f32_16x16x32_bf16 v[108:111], v[124:127], v[116:119], v[108:111]
	v_mfma_f32_16x16x32_bf16 v[92:95], v[128:131], v[116:119], v[92:95]
	s_waitcnt lgkmcnt(0)
	v_mfma_f32_16x16x32_bf16 v[40:43], v[96:99], v[120:123], v[40:43]
	v_mfma_f32_16x16x32_bf16 v[44:47], v[112:115], v[120:123], v[44:47]
	v_mfma_f32_16x16x32_bf16 v[60:63], v[124:127], v[120:123], v[60:63]
	v_mfma_f32_16x16x32_bf16 v[72:75], v[128:131], v[120:123], v[72:75]
	s_waitcnt vmcnt(11)
	ds_write_b128 v12, v[16:19] offset:49152
	s_waitcnt vmcnt(10)
	ds_write_b128 v12, v[20:23] offset:57344
	s_waitcnt vmcnt(9)
	ds_write_b128 v136, v[24:27] offset:16384
	s_waitcnt vmcnt(8)
	ds_write_b128 v136, v[28:31] offset:24576
	s_waitcnt vmcnt(7)
	ds_write_b128 v64, v[32:35]
	s_waitcnt vmcnt(6)
	ds_write_b128 v64, v[36:39] offset:8192
	s_waitcnt lgkmcnt(0)
	s_barrier
	global_load_dwordx4 v[176:179], v[0:1], off offset:896
	global_load_dwordx4 v[180:183], v[2:3], off offset:896
	global_load_dwordx4 v[184:187], v[4:5], off offset:896
	global_load_dwordx4 v[188:191], v[6:7], off offset:896
	global_load_dwordx4 v[192:195], v[8:9], off offset:896
	global_load_dwordx4 v[196:199], v[10:11], off offset:896
	ds_read_b128 v[96:99], v15
	ds_read_b128 v[112:115], v15 offset:2048
	ds_read_b128 v[116:119], v13 offset:49152
	ds_read_b128 v[120:123], v13 offset:51200
	ds_read_b128 v[124:127], v15 offset:4096
	ds_read_b128 v[128:131], v15 offset:6144
	s_waitcnt lgkmcnt(3)
	v_mfma_f32_16x16x32_bf16 v[56:59], v[96:99], v[116:119], v[56:59]
	v_mfma_f32_16x16x32_bf16 v[68:71], v[112:115], v[116:119], v[68:71]
	s_waitcnt lgkmcnt(1)
	v_mfma_f32_16x16x32_bf16 v[76:79], v[124:127], v[116:119], v[76:79]
	s_waitcnt lgkmcnt(0)
	v_mfma_f32_16x16x32_bf16 v[48:51], v[128:131], v[116:119], v[48:51]
	v_mfma_f32_16x16x32_bf16 v[80:83], v[96:99], v[120:123], v[80:83]
	v_mfma_f32_16x16x32_bf16 v[84:87], v[112:115], v[120:123], v[84:87]
	v_mfma_f32_16x16x32_bf16 v[88:91], v[124:127], v[120:123], v[88:91]
	v_mfma_f32_16x16x32_bf16 v[52:55], v[128:131], v[120:123], v[52:55]
	ds_read_b128 v[116:119], v13 offset:53248
	ds_read_b128 v[120:123], v13 offset:55296
	s_waitcnt lgkmcnt(1)
	v_mfma_f32_16x16x32_bf16 v[100:103], v[96:99], v[116:119], v[100:103]
	v_mfma_f32_16x16x32_bf16 v[104:107], v[112:115], v[116:119], v[104:107]
	v_mfma_f32_16x16x32_bf16 v[108:111], v[124:127], v[116:119], v[108:111]
	v_mfma_f32_16x16x32_bf16 v[92:95], v[128:131], v[116:119], v[92:95]
	s_waitcnt lgkmcnt(0)
	v_mfma_f32_16x16x32_bf16 v[40:43], v[96:99], v[120:123], v[40:43]
	ds_read_b128 v[96:99], v132
	v_mfma_f32_16x16x32_bf16 v[44:47], v[112:115], v[120:123], v[44:47]
	v_mfma_f32_16x16x32_bf16 v[60:63], v[124:127], v[120:123], v[60:63]
	v_mfma_f32_16x16x32_bf16 v[72:75], v[128:131], v[120:123], v[72:75]
	ds_read_b128 v[112:115], v132 offset:2048
	ds_read_b128 v[116:119], v14 offset:49152
	ds_read_b128 v[120:123], v14 offset:51200
	ds_read_b128 v[124:127], v132 offset:4096
	ds_read_b128 v[128:131], v132 offset:6144
	s_waitcnt lgkmcnt(3)
	v_mfma_f32_16x16x32_bf16 v[56:59], v[96:99], v[116:119], v[56:59]
	v_mfma_f32_16x16x32_bf16 v[68:71], v[112:115], v[116:119], v[68:71]
	s_waitcnt lgkmcnt(1)
	v_mfma_f32_16x16x32_bf16 v[76:79], v[124:127], v[116:119], v[76:79]
	s_waitcnt lgkmcnt(0)
	v_mfma_f32_16x16x32_bf16 v[48:51], v[128:131], v[116:119], v[48:51]
	v_mfma_f32_16x16x32_bf16 v[80:83], v[96:99], v[120:123], v[80:83]
	v_mfma_f32_16x16x32_bf16 v[84:87], v[112:115], v[120:123], v[84:87]
	v_mfma_f32_16x16x32_bf16 v[88:91], v[124:127], v[120:123], v[88:91]
	v_mfma_f32_16x16x32_bf16 v[52:55], v[128:131], v[120:123], v[52:55]
	ds_read_b128 v[116:119], v14 offset:53248
	ds_read_b128 v[120:123], v14 offset:55296
	s_waitcnt lgkmcnt(1)
	v_mfma_f32_16x16x32_bf16 v[100:103], v[96:99], v[116:119], v[100:103]
	v_mfma_f32_16x16x32_bf16 v[104:107], v[112:115], v[116:119], v[104:107]
	v_mfma_f32_16x16x32_bf16 v[108:111], v[124:127], v[116:119], v[108:111]
	v_mfma_f32_16x16x32_bf16 v[92:95], v[128:131], v[116:119], v[92:95]
	s_waitcnt lgkmcnt(0)
	v_mfma_f32_16x16x32_bf16 v[40:43], v[96:99], v[120:123], v[40:43]
	v_mfma_f32_16x16x32_bf16 v[44:47], v[112:115], v[120:123], v[44:47]
	v_mfma_f32_16x16x32_bf16 v[60:63], v[124:127], v[120:123], v[60:63]
	v_mfma_f32_16x16x32_bf16 v[72:75], v[128:131], v[120:123], v[72:75]
	s_waitcnt vmcnt(11)
	ds_write_b128 v12, v[200:203]
	s_waitcnt vmcnt(10)
	ds_write_b128 v12, v[204:207] offset:8192
	s_waitcnt vmcnt(9)
	ds_write_b128 v12, v[208:211] offset:16384
	s_waitcnt vmcnt(8)
	ds_write_b128 v12, v[212:215] offset:24576
	s_waitcnt vmcnt(7)
	ds_write_b128 v12, v[216:219] offset:32768
	s_waitcnt vmcnt(6)
	ds_write_b128 v12, v[220:223] offset:40960
	s_waitcnt lgkmcnt(0)
	s_barrier
	s_nop 0
	s_nop 0
	s_nop 0
	s_nop 0
	s_nop 0
	ds_read_b128 v[28:31], v133 offset:32768
	ds_read_b128 v[32:35], v133 offset:34816
	ds_read_b128 v[36:39], v13
	ds_read_b128 v[96:99], v13 offset:2048
	ds_read_b128 v[112:115], v133 offset:36864
	ds_read_b128 v[116:119], v133 offset:38912
	s_waitcnt lgkmcnt(3)
	v_mfma_f32_16x16x32_bf16 v[56:59], v[28:31], v[36:39], v[56:59]
	v_mfma_f32_16x16x32_bf16 v[68:71], v[32:35], v[36:39], v[68:71]
	s_waitcnt lgkmcnt(1)
	v_mfma_f32_16x16x32_bf16 v[76:79], v[112:115], v[36:39], v[76:79]
	s_waitcnt lgkmcnt(0)
	v_mfma_f32_16x16x32_bf16 v[36:39], v[116:119], v[36:39], v[48:51]
	v_mfma_f32_16x16x32_bf16 v[48:51], v[28:31], v[96:99], v[80:83]
	v_mfma_f32_16x16x32_bf16 v[80:83], v[32:35], v[96:99], v[84:87]
	v_mfma_f32_16x16x32_bf16 v[84:87], v[112:115], v[96:99], v[88:91]
	v_mfma_f32_16x16x32_bf16 v[52:55], v[116:119], v[96:99], v[52:55]
	s_nop 1
	ds_read_b128 v[88:91], v13 offset:4096
	ds_read_b128 v[96:99], v13 offset:6144
	s_waitcnt lgkmcnt(1)
	v_mfma_f32_16x16x32_bf16 v[100:103], v[28:31], v[88:91], v[100:103]
	v_mfma_f32_16x16x32_bf16 v[104:107], v[32:35], v[88:91], v[104:107]
	v_mfma_f32_16x16x32_bf16 v[108:111], v[112:115], v[88:91], v[108:111]
	v_mfma_f32_16x16x32_bf16 v[88:91], v[116:119], v[88:91], v[92:95]
	s_waitcnt lgkmcnt(0)
	v_mfma_f32_16x16x32_bf16 v[28:31], v[28:31], v[96:99], v[40:43]
	v_mfma_f32_16x16x32_bf16 v[32:35], v[32:35], v[96:99], v[44:47]
	v_mfma_f32_16x16x32_bf16 v[40:43], v[112:115], v[96:99], v[60:63]
	s_nop 1
	ds_read_b128 v[44:47], v135 offset:32768
	v_mfma_f32_16x16x32_bf16 v[60:63], v[116:119], v[96:99], v[72:75]
	s_nop 2
	ds_read_b128 v[72:75], v135 offset:34816
	ds_read_b128 v[92:95], v14
	ds_read_b128 v[96:99], v14 offset:2048
	ds_read_b128 v[112:115], v135 offset:36864
	ds_read_b128 v[116:119], v135 offset:38912
	s_waitcnt lgkmcnt(3)
	v_mfma_f32_16x16x32_bf16 v[56:59], v[44:47], v[92:95], v[56:59]
	v_mfma_f32_16x16x32_bf16 v[68:71], v[72:75], v[92:95], v[68:71]
	s_waitcnt lgkmcnt(1)
	v_mfma_f32_16x16x32_bf16 v[76:79], v[112:115], v[92:95], v[76:79]
	s_waitcnt lgkmcnt(0)
	v_mfma_f32_16x16x32_bf16 v[36:39], v[116:119], v[92:95], v[36:39]
	v_mfma_f32_16x16x32_bf16 v[48:51], v[44:47], v[96:99], v[48:51]
	v_mfma_f32_16x16x32_bf16 v[80:83], v[72:75], v[96:99], v[80:83]
	v_mfma_f32_16x16x32_bf16 v[84:87], v[112:115], v[96:99], v[84:87]
	v_mfma_f32_16x16x32_bf16 v[52:55], v[116:119], v[96:99], v[52:55]
	ds_read_b128 v[92:95], v14 offset:4096
	ds_read_b128 v[96:99], v14 offset:6144
	s_waitcnt lgkmcnt(1)
	v_mfma_f32_16x16x32_bf16 v[100:103], v[44:47], v[92:95], v[100:103]
	v_mfma_f32_16x16x32_bf16 v[104:107], v[72:75], v[92:95], v[104:107]
	v_mfma_f32_16x16x32_bf16 v[108:111], v[112:115], v[92:95], v[108:111]
	v_mfma_f32_16x16x32_bf16 v[88:91], v[116:119], v[92:95], v[88:91]
	s_waitcnt lgkmcnt(0)
	v_mfma_f32_16x16x32_bf16 v[28:31], v[44:47], v[96:99], v[28:31]
	v_mfma_f32_16x16x32_bf16 v[32:35], v[72:75], v[96:99], v[32:35]
	v_mfma_f32_16x16x32_bf16 v[40:43], v[112:115], v[96:99], v[40:43]
	v_mfma_f32_16x16x32_bf16 v[44:47], v[116:119], v[96:99], v[60:63]
	s_waitcnt vmcnt(5)
	ds_write_b128 v12, v[176:179] offset:49152
	s_waitcnt vmcnt(4)
	ds_write_b128 v12, v[180:183] offset:57344
	s_waitcnt vmcnt(3)
	ds_write_b128 v136, v[184:187] offset:16384
	s_waitcnt vmcnt(2)
	ds_write_b128 v136, v[188:191] offset:24576
	s_waitcnt vmcnt(1)
	ds_write_b128 v64, v[192:195]
	s_waitcnt vmcnt(0)
	ds_write_b128 v64, v[196:199] offset:8192
	s_waitcnt lgkmcnt(0)
	s_barrier
	ds_read_b128 v[0:3], v15
	ds_read_b128 v[4:7], v15 offset:2048
	ds_read_b128 v[8:11], v13 offset:49152
	ds_read_b128 v[16:19], v13 offset:51200
	ds_read_b128 v[24:27], v15 offset:4096
	ds_read_b128 v[60:63], v15 offset:6144
	s_waitcnt lgkmcnt(3)
	v_mfma_f32_16x16x32_bf16 v[20:23], v[0:3], v[8:11], v[56:59]
	v_mfma_f32_16x16x32_bf16 v[56:59], v[4:7], v[8:11], v[68:71]
	s_waitcnt lgkmcnt(1)
	v_mfma_f32_16x16x32_bf16 v[68:71], v[24:27], v[8:11], v[76:79]
	s_waitcnt lgkmcnt(0)
	v_mfma_f32_16x16x32_bf16 v[8:11], v[60:63], v[8:11], v[36:39]
	v_mfma_f32_16x16x32_bf16 v[36:39], v[0:3], v[16:19], v[48:51]
	v_mfma_f32_16x16x32_bf16 v[48:51], v[4:7], v[16:19], v[80:83]
	v_mfma_f32_16x16x32_bf16 v[72:75], v[24:27], v[16:19], v[84:87]
	v_mfma_f32_16x16x32_bf16 v[16:19], v[60:63], v[16:19], v[52:55]
	s_nop 2
	ds_read_b128 v[52:55], v13 offset:53248
	ds_read_b128 v[76:79], v13 offset:55296
	s_waitcnt lgkmcnt(1)
	v_mfma_f32_16x16x32_bf16 v[80:83], v[0:3], v[52:55], v[100:103]
	v_mfma_f32_16x16x32_bf16 v[84:87], v[4:7], v[52:55], v[104:107]
	v_mfma_f32_16x16x32_bf16 v[92:95], v[24:27], v[52:55], v[108:111]
	v_mfma_f32_16x16x32_bf16 v[52:55], v[60:63], v[52:55], v[88:91]
	s_waitcnt lgkmcnt(0)
	v_mfma_f32_16x16x32_bf16 v[0:3], v[0:3], v[76:79], v[28:31]
	v_mfma_f32_16x16x32_bf16 v[4:7], v[4:7], v[76:79], v[32:35]
	s_nop 1
	ds_read_b128 v[28:31], v132
	v_mfma_f32_16x16x32_bf16 v[24:27], v[24:27], v[76:79], v[40:43]
	v_mfma_f32_16x16x32_bf16 v[32:35], v[60:63], v[76:79], v[44:47]
	s_nop 1
	ds_read_b128 v[40:43], v132 offset:2048
	ds_read_b128 v[44:47], v14 offset:49152
	ds_read_b128 v[60:63], v14 offset:51200
	ds_read_b128 v[76:79], v132 offset:4096
	ds_read_b128 v[88:91], v132 offset:6144
	s_waitcnt lgkmcnt(3)
	v_mfma_f32_16x16x32_bf16 v[20:23], v[28:31], v[44:47], v[20:23]
	v_mfma_f32_16x16x32_bf16 v[56:59], v[40:43], v[44:47], v[56:59]
	s_waitcnt lgkmcnt(1)
	v_mfma_f32_16x16x32_bf16 v[68:71], v[76:79], v[44:47], v[68:71]
	s_waitcnt lgkmcnt(0)
	v_mfma_f32_16x16x32_bf16 v[8:11], v[88:91], v[44:47], v[8:11]
	v_mfma_f32_16x16x32_bf16 v[36:39], v[28:31], v[60:63], v[36:39]
	v_mfma_f32_16x16x32_bf16 v[44:47], v[40:43], v[60:63], v[48:51]
	v_mfma_f32_16x16x32_bf16 v[48:51], v[76:79], v[60:63], v[72:75]
	v_mfma_f32_16x16x32_bf16 v[16:19], v[88:91], v[60:63], v[16:19]
	ds_read_b128 v[60:63], v14 offset:53248
	ds_read_b128 v[12:15], v14 offset:55296
	s_waitcnt lgkmcnt(1)
	v_mfma_f32_16x16x32_bf16 v[72:75], v[28:31], v[60:63], v[80:83]
	v_mfma_f32_16x16x32_bf16 v[80:83], v[40:43], v[60:63], v[84:87]
	v_mfma_f32_16x16x32_bf16 v[84:87], v[76:79], v[60:63], v[92:95]
	v_mfma_f32_16x16x32_bf16 v[52:55], v[88:91], v[60:63], v[52:55]
	s_waitcnt lgkmcnt(0)
	v_mfma_f32_16x16x32_bf16 v[0:3], v[28:31], v[12:15], v[0:3]
	v_mfma_f32_16x16x32_bf16 v[4:7], v[40:43], v[12:15], v[4:7]
	v_mfma_f32_16x16x32_bf16 v[24:27], v[76:79], v[12:15], v[24:27]
	v_mfma_f32_16x16x32_bf16 v[12:15], v[88:91], v[12:15], v[32:35]
	s_add_i32 s31, s31, s4
	s_or_b32 s4, s6, s5
	s_ashr_i32 s5, s31, 31
	v_mov_b32_e32 v30, v238
	s_barrier
	v_mov_b32_e32 v29, s5
	v_and_or_b32 v28, v30, 15, s31
	v_lshlrev_b64 v[28:29], 10, v[28:29]
	v_lshl_add_u64 v[28:29], s[16:17], 0, v[28:29]
	s_lshl_b32 s6, s4, 2
	v_lshl_add_u64 v[28:29], v[28:29], 0, s[6:7]
	v_and_b32_e32 v64, 48, v30
	v_lshl_add_u64 v[28:29], v[28:29], 0, v[64:65]
	global_store_dwordx4 v[28:29], v[20:23], off
	global_store_dwordx4 v[28:29], v[56:59], off offset:64
	global_store_dwordx4 v[28:29], v[68:71], off offset:128
	global_store_dwordx4 v[28:29], v[8:11], off offset:192
	s_nop 1
	v_add_co_u32_e32 v10, vcc, s29, v28
	v_lshl_add_u64 v[8:9], v[28:29], 0, s[10:11]
	s_nop 0
	v_addc_co_u32_e32 v11, vcc, 0, v29, vcc
	global_store_dwordx4 v[10:11], v[36:39], off
	global_store_dwordx4 v[8:9], v[44:47], off offset:64
	global_store_dwordx4 v[8:9], v[48:51], off offset:128
	global_store_dwordx4 v[8:9], v[16:19], off offset:192
	v_add_co_u32_e32 v10, vcc, 0x8000, v28
	v_lshl_add_u64 v[8:9], v[28:29], 0, s[12:13]
	s_nop 0
	v_addc_co_u32_e32 v11, vcc, 0, v29, vcc
	global_store_dwordx4 v[10:11], v[72:75], off
	global_store_dwordx4 v[8:9], v[80:83], off offset:64
	global_store_dwordx4 v[8:9], v[84:87], off offset:128
	global_store_dwordx4 v[8:9], v[52:55], off offset:192
	v_add_co_u32_e32 v10, vcc, 0xc000, v28
	v_lshl_add_u64 v[8:9], v[28:29], 0, s[14:15]
	s_nop 0
	v_addc_co_u32_e32 v11, vcc, 0, v29, vcc
	global_store_dwordx4 v[10:11], v[0:3], off
	global_store_dwordx4 v[8:9], v[4:7], off offset:64
	global_store_dwordx4 v[8:9], v[24:27], off offset:128
	global_store_dwordx4 v[8:9], v[12:15], off offset:192
	s_branch .LBB0_620
